# speedup vs baseline: 1.0174x; 1.0009x over previous
; __device__ __forceinline__ void attn_phase(LAS unsigned char* lds, bf16_t* Qb, const bf16_t* KVb, const bf16_t* GZ, const float* sinkp) {
;     ...
;                     float mx = __builtin_fmaxf(s0[0], s1[0]);
; #pragma unroll
;                     for (int r = 1; r < 16; ++r) { float t_; asm("v_max3_f32 %0, %1, %2, %3" : "=v"(t_) : "v"(mx), "v"(s0[r]), "v"(s1[r])); mx = t_; }
;                     mx = fmaxf(mx, __shfl_xor(mx, 32));
;                     const float mx2 = mx * SC;
;                     const bool bump = mx2 > m_run + 8.f;
;                     if (__any(bump)) {
;                         const float m_new = bump ? mx2 : m_run, alpha = __builtin_amdgcn_exp2f(m_run - m_new);
;                         m_run = m_new; l_run *= alpha;
; #pragma unroll
;                         for (int dt = 0; dt < 4; ++dt)
; #pragma unroll
;                             for (int r = 0; r < 16; ++r) o[dt][r] *= alpha;
;                     }
.LBB0_176:
	s_nop 9
	v_max_f32_e32 v177, v64, v64
	v_max_f32_e32 v178, v80, v80
	v_max_f32_e32 v177, v178, v177
	v_max3_f32 v177, v177, v81, v65
	s_nop 0
	v_max3_f32 v177, v177, v82, v66
	s_nop 0
	v_max3_f32 v177, v177, v83, v67
	s_nop 0
	v_max3_f32 v177, v177, v84, v68
	s_nop 0
	v_max3_f32 v177, v177, v85, v69
	s_nop 0
	v_max3_f32 v177, v177, v86, v70
	s_nop 0
	v_max3_f32 v177, v177, v87, v71
	s_nop 0
	v_max3_f32 v177, v177, v88, v72
	s_nop 0
	v_max3_f32 v177, v177, v89, v73
	s_nop 0
	v_max3_f32 v177, v177, v90, v74
	s_nop 0
	v_max3_f32 v177, v177, v91, v75
	s_nop 0
	v_max3_f32 v177, v177, v92, v76
	s_nop 0
	v_max3_f32 v177, v177, v93, v77
	s_nop 0
	v_max3_f32 v177, v177, v94, v78
	s_nop 0
	v_max3_f32 v177, v177, v95, v79
	v_max_f32_e32 v177, v177, v177
	v_mov_b32_e32 v178, v177
	s_nop 1
	v_permlane32_swap_b32_e32 v178, v177
	v_max_f32_e32 v177, v177, v178
	v_mul_f32_e32 v177, 0x3e0293ee, v177
	v_add_f32_e32 v178, 0x41000000, v176
	v_cmp_gt_f32_e32 vcc, v177, v178
	s_cbranch_vccz .LBB0_178
	s_nop 0
	v_cndmask_b32_e32 v177, v176, v177, vcc
	v_sub_f32_e32 v176, v176, v177
	v_exp_f32_e32 v176, v176
	s_nop 0
	v_pk_mul_f32 v[62:63], v[62:63], v[176:177] op_sel_hi:[1,0]
	v_pk_mul_f32 v[60:61], v[60:61], v[176:177] op_sel_hi:[1,0]
	v_pk_mul_f32 v[58:59], v[58:59], v[176:177] op_sel_hi:[1,0]
	v_pk_mul_f32 v[56:57], v[56:57], v[176:177] op_sel_hi:[1,0]
	v_pk_mul_f32 v[54:55], v[54:55], v[176:177] op_sel_hi:[1,0]
	v_pk_mul_f32 v[52:53], v[52:53], v[176:177] op_sel_hi:[1,0]
	v_pk_mul_f32 v[50:51], v[50:51], v[176:177] op_sel_hi:[1,0]
	v_pk_mul_f32 v[48:49], v[48:49], v[176:177] op_sel_hi:[1,0]
	v_pk_mul_f32 v[46:47], v[46:47], v[176:177] op_sel_hi:[1,0]
	v_pk_mul_f32 v[44:45], v[44:45], v[176:177] op_sel_hi:[1,0]
	v_pk_mul_f32 v[42:43], v[42:43], v[176:177] op_sel_hi:[1,0]
	v_pk_mul_f32 v[40:41], v[40:41], v[176:177] op_sel_hi:[1,0]
	v_pk_mul_f32 v[38:39], v[38:39], v[176:177] op_sel_hi:[1,0]
	v_pk_mul_f32 v[36:37], v[36:37], v[176:177] op_sel_hi:[1,0]
	v_pk_mul_f32 v[34:35], v[34:35], v[176:177] op_sel_hi:[1,0]
	v_pk_mul_f32 v[32:33], v[32:33], v[176:177] op_sel_hi:[1,0]
	v_pk_mul_f32 v[30:31], v[30:31], v[176:177] op_sel_hi:[1,0]
	v_pk_mul_f32 v[28:29], v[28:29], v[176:177] op_sel_hi:[1,0]
	v_pk_mul_f32 v[26:27], v[26:27], v[176:177] op_sel_hi:[1,0]
	v_pk_mul_f32 v[24:25], v[24:25], v[176:177] op_sel_hi:[1,0]
	v_pk_mul_f32 v[22:23], v[22:23], v[176:177] op_sel_hi:[1,0]
	v_pk_mul_f32 v[20:21], v[20:21], v[176:177] op_sel_hi:[1,0]
	v_pk_mul_f32 v[18:19], v[18:19], v[176:177] op_sel_hi:[1,0]
	v_pk_mul_f32 v[16:17], v[16:17], v[176:177] op_sel_hi:[1,0]
	v_pk_mul_f32 v[14:15], v[14:15], v[176:177] op_sel_hi:[1,0]
	v_pk_mul_f32 v[12:13], v[12:13], v[176:177] op_sel_hi:[1,0]
	v_pk_mul_f32 v[10:11], v[10:11], v[176:177] op_sel_hi:[1,0]
	v_pk_mul_f32 v[8:9], v[8:9], v[176:177] op_sel_hi:[1,0]
	v_pk_mul_f32 v[6:7], v[6:7], v[176:177] op_sel_hi:[1,0]
	v_pk_mul_f32 v[4:5], v[4:5], v[176:177] op_sel_hi:[1,0]
	v_pk_mul_f32 v[2:3], v[2:3], v[176:177] op_sel_hi:[1,0]
	v_pk_mul_f32 v[0:1], v[0:1], v[176:177] op_sel_hi:[1,0]
	v_mul_f32_e32 v173, v173, v176
	v_mov_b32_e32 v176, v177
; __device__ __forceinline__ void attn_phase(LAS unsigned char* lds, bf16_t* Qb, const bf16_t* KVb, const bf16_t* GZ, const float* sinkp) {
;     ...
;                     float rs = 0.f;
; #pragma unroll
;                     for (int r = 0; r < 16; ++r) { s0[r] = __builtin_amdgcn_exp2f(__builtin_fmaf(s0[r], SC, -m_run)); s1[r] = __builtin_amdgcn_exp2f(__builtin_fmaf(s1[r], SC, -m_run)); rs += s0[r] + s1[r]; }
;                     rs += __shfl_xor(rs, 32);
;                     l_run += rs;
;                     {
;                         bf16x8 pf[4];
; #pragma unroll
;                         for (int c = 0; c < 4; ++c) {
;                             const int s8 = 8 * (c & 1); u32x4 pw;
;                             if (c < 2) { pw.x = cvt_pk_bf16(s0[s8], s0[s8 + 1]); pw.y = cvt_pk_bf16(s0[s8 + 2], s0[s8 + 3]); pw.z = cvt_pk_bf16(s0[s8 + 4], s0[s8 + 5]); pw.w = cvt_pk_bf16(s0[s8 + 6], s0[s8 + 7]); }
;                             else { pw.x = cvt_pk_bf16(s1[s8], s1[s8 + 1]); pw.y = cvt_pk_bf16(s1[s8 + 2], s1[s8 + 3]); pw.z = cvt_pk_bf16(s1[s8 + 4], s1[s8 + 5]); pw.w = cvt_pk_bf16(s1[s8 + 6], s1[s8 + 7]); }
;                             pf[c] = __builtin_bit_cast(bf16x8, pw);
;                         }
;                         s16x4 va[2][4][2];
; #pragma unroll
;                         for (int dt = 0; dt < 4; ++dt) { va[0][dt][0] = __builtin_amdgcn_ds_read_tr16_b64_v4i16((LAS s16x4*)(Vc + vaddr[dt][0])); va[0][dt][1] = __builtin_amdgcn_ds_read_tr16_b64_v4i16((LAS s16x4*)(Vc + vaddr[dt][1])); }
;                         __builtin_amdgcn_sched_barrier(0);
; #pragma unroll
;                         for (int c = 0; c < 4; ++c) {
;                             if (c < 3) {
; #pragma unroll
;                                 for (int dt = 0; dt < 4; ++dt) { va[(c + 1) & 1][dt][0] = __builtin_amdgcn_ds_read_tr16_b64_v4i16((LAS s16x4*)(Vc + vaddr[dt][0] + (c + 1) * 4096)); va[(c + 1) & 1][dt][1] = __builtin_amdgcn_ds_read_tr16_b64_v4i16((LAS s16x4*)(Vc + vaddr[dt][1] + (c + 1) * 4096)); }
;                             }
;                             __builtin_amdgcn_sched_barrier(0);
; #pragma unroll
;                             for (int dt = 0; dt < 4; ++dt) {
;                                 const s16x4 a0 = va[c & 1][dt][0], a1 = va[c & 1][dt][1];
;                                 const bf16x8 a = {a0[0], a0[1], a0[2], a0[3], a1[0], a1[1], a1[2], a1[3]};
.LBB0_178:
	v_fma_f32 v80, v80, s82, -v176
	v_fma_f32 v64, v64, s82, -v176
	v_exp_f32_e32 v177, v80
	v_exp_f32_e32 v178, v64
	v_fma_f32 v80, v81, s82, -v176
	v_fma_f32 v65, v65, s82, -v176
	v_exp_f32_e32 v179, v80
	v_exp_f32_e32 v180, v65
	v_add_f32_e32 v64, v177, v178
	v_add_f32_e32 v64, 0, v64
	v_add_u32_e32 v202, s3, v163
	v_add_f32_e32 v65, v179, v180
	v_add_f32_e32 v64, v65, v64
	v_fma_f32 v65, v82, s82, -v176
	v_exp_f32_e32 v181, v65
	v_fma_f32 v65, v66, s82, -v176
	v_exp_f32_e32 v182, v65
	v_add_u32_e32 v203, s3, v164
	v_add_u32_e32 v204, s3, v165
	v_add_u32_e32 v205, s3, v166
	v_add_f32_e32 v65, v181, v182
	v_add_f32_e32 v64, v65, v64
	v_fma_f32 v65, v83, s82, -v176
	v_exp_f32_e32 v66, v65
	v_fma_f32 v65, v67, s82, -v176
	v_exp_f32_e32 v183, v65
	v_add_u32_e32 v206, s3, v167
	v_add_u32_e32 v207, s3, v168
	v_add_f32_e32 v65, v66, v183
	v_add_f32_e32 v64, v65, v64
	v_fma_f32 v65, v84, s82, -v176
	v_exp_f32_e32 v67, v65
	v_fma_f32 v65, v68, s82, -v176
	v_exp_f32_e32 v184, v65
	s_nop 0
	v_add_f32_e32 v65, v67, v184
	v_add_f32_e32 v64, v65, v64
	v_fma_f32 v65, v85, s82, -v176
	v_exp_f32_e32 v185, v65
	v_fma_f32 v65, v69, s82, -v176
	v_exp_f32_e32 v186, v65
	s_nop 0
	v_add_f32_e32 v65, v185, v186
	v_add_f32_e32 v82, v65, v64
	v_fma_f32 v64, v86, s82, -v176
	v_exp_f32_e32 v69, v64
	v_fma_f32 v64, v70, s82, -v176
	v_exp_f32_e32 v81, v64
	v_fma_f32 v64, v87, s82, -v176
	v_exp_f32_e32 v68, v64
	v_fma_f32 v64, v71, s82, -v176
	v_exp_f32_e32 v80, v64
	s_nop 0
	v_pk_add_f32 v[64:65], v[68:69], v[80:81]
	s_nop 0
	v_add_f32_e32 v65, v65, v82
	v_add_f32_e32 v84, v64, v65
	v_fma_f32 v64, v88, s82, -v176
	v_exp_f32_e32 v71, v64
	v_fma_f32 v64, v72, s82, -v176
	v_exp_f32_e32 v83, v64
	v_fma_f32 v64, v89, s82, -v176
	v_exp_f32_e32 v70, v64
	v_fma_f32 v64, v73, s82, -v176
	v_exp_f32_e32 v82, v64
	s_nop 0
	v_pk_add_f32 v[64:65], v[70:71], v[82:83]
	s_nop 0
	v_add_f32_e32 v65, v65, v84
	v_add_f32_e32 v86, v64, v65
	v_fma_f32 v64, v90, s82, -v176
	v_exp_f32_e32 v73, v64
	v_fma_f32 v64, v74, s82, -v176
	v_exp_f32_e32 v85, v64
	v_fma_f32 v64, v91, s82, -v176
	v_exp_f32_e32 v72, v64
	v_fma_f32 v64, v75, s82, -v176
	v_exp_f32_e32 v84, v64
	s_nop 0
	v_pk_add_f32 v[64:65], v[72:73], v[84:85]
	s_nop 0
	v_add_f32_e32 v65, v65, v86
	v_add_f32_e32 v88, v64, v65
	v_fma_f32 v64, v92, s82, -v176
	v_exp_f32_e32 v75, v64
	v_fma_f32 v64, v76, s82, -v176
	v_exp_f32_e32 v87, v64
	v_fma_f32 v64, v93, s82, -v176
	v_exp_f32_e32 v74, v64
	v_fma_f32 v64, v77, s82, -v176
	v_exp_f32_e32 v86, v64
	s_nop 0
	v_pk_add_f32 v[64:65], v[74:75], v[86:87]
	s_nop 0
	v_add_f32_e32 v65, v65, v88
	v_add_f32_e32 v90, v64, v65
	v_fma_f32 v64, v94, s82, -v176
	v_exp_f32_e32 v77, v64
	v_fma_f32 v64, v78, s82, -v176
	v_exp_f32_e32 v89, v64
	v_fma_f32 v64, v95, s82, -v176
	v_exp_f32_e32 v76, v64
	v_fma_f32 v64, v79, s82, -v176
	v_exp_f32_e32 v88, v64
	s_nop 0
	v_pk_add_f32 v[64:65], v[76:77], v[88:89]
	s_nop 0
	v_add_f32_e32 v65, v65, v90
	v_add_f32_e32 v64, v64, v65
	v_mov_b32_e32 v65, v64
	s_nop 1
	v_permlane32_swap_b32_e32 v65, v64
	v_add_f32_e32 v187, v64, v65
	v_cvt_pk_bf16_f32 v64, v177, v179
	v_cvt_pk_bf16_f32 v65, v181, v66
	v_cvt_pk_bf16_f32 v66, v67, v185
	v_cvt_pk_bf16_f32 v67, v69, v68
	v_cvt_pk_bf16_f32 v68, v71, v70
	v_cvt_pk_bf16_f32 v69, v73, v72
	v_cvt_pk_bf16_f32 v70, v75, v74
	v_cvt_pk_bf16_f32 v71, v77, v76
	v_cvt_pk_bf16_f32 v72, v178, v180
	v_cvt_pk_bf16_f32 v73, v182, v183
	v_cvt_pk_bf16_f32 v74, v184, v186
	v_add_u32_e32 v177, s3, v161
	v_add_u32_e32 v186, s3, v162
	v_cvt_pk_bf16_f32 v75, v81, v80
	v_cvt_pk_bf16_f32 v76, v83, v82
	v_cvt_pk_bf16_f32 v77, v85, v84
	v_cvt_pk_bf16_f32 v78, v87, v86
	v_cvt_pk_bf16_f32 v79, v89, v88
	ds_read_b64_tr_b16 v[80:81], v177 offset:16384
	ds_read_b64_tr_b16 v[82:83], v186 offset:16384
	ds_read_b64_tr_b16 v[84:85], v202 offset:16384
	ds_read_b64_tr_b16 v[86:87], v203 offset:16384
	ds_read_b64_tr_b16 v[88:89], v204 offset:16384
	ds_read_b64_tr_b16 v[90:91], v205 offset:16384
	ds_read_b64_tr_b16 v[92:93], v206 offset:16384
	ds_read_b64_tr_b16 v[94:95], v207 offset:16384
	ds_read_b64_tr_b16 v[178:179], v177 offset:20480
	ds_read_b64_tr_b16 v[180:181], v186 offset:20480
	ds_read_b64_tr_b16 v[182:183], v202 offset:20480
	ds_read_b64_tr_b16 v[184:185], v203 offset:20480
	ds_read_b64_tr_b16 v[194:195], v204 offset:20480
	ds_read_b64_tr_b16 v[196:197], v205 offset:20480
	ds_read_b64_tr_b16 v[198:199], v206 offset:20480
	ds_read_b64_tr_b16 v[200:201], v207 offset:20480
	s_waitcnt lgkmcnt(14)
	v_mfma_f32_32x32x16_bf16 v[48:63], v[80:83], v[64:67], v[48:63]
	s_waitcnt lgkmcnt(12)
	v_mfma_f32_32x32x16_bf16 v[32:47], v[84:87], v[64:67], v[32:47]
	s_waitcnt lgkmcnt(10)
	v_mfma_f32_32x32x16_bf16 v[16:31], v[88:91], v[64:67], v[16:31]
	s_waitcnt lgkmcnt(8)
	v_mfma_f32_32x32x16_bf16 v[0:15], v[92:95], v[64:67], v[0:15]
	ds_read_b64_tr_b16 v[64:65], v177 offset:24576
	ds_read_b64_tr_b16 v[66:67], v186 offset:24576
	ds_read_b64_tr_b16 v[80:81], v202 offset:24576
	ds_read_b64_tr_b16 v[82:83], v203 offset:24576
	ds_read_b64_tr_b16 v[84:85], v204 offset:24576
	ds_read_b64_tr_b16 v[86:87], v205 offset:24576
	ds_read_b64_tr_b16 v[88:89], v206 offset:24576
	ds_read_b64_tr_b16 v[90:91], v207 offset:24576
	s_waitcnt lgkmcnt(14)
	v_mfma_f32_32x32x16_bf16 v[48:63], v[178:181], v[68:71], v[48:63]
	s_waitcnt lgkmcnt(12)
	v_mfma_f32_32x32x16_bf16 v[32:47], v[182:185], v[68:71], v[32:47]
	s_waitcnt lgkmcnt(10)
	v_mfma_f32_32x32x16_bf16 v[16:31], v[194:197], v[68:71], v[16:31]
	s_waitcnt lgkmcnt(8)
	v_mfma_f32_32x32x16_bf16 v[0:15], v[198:201], v[68:71], v[0:15]
	ds_read_b64_tr_b16 v[68:69], v177 offset:28672
	ds_read_b64_tr_b16 v[70:71], v186 offset:28672
	ds_read_b64_tr_b16 v[92:93], v202 offset:28672
	ds_read_b64_tr_b16 v[94:95], v203 offset:28672
	ds_read_b64_tr_b16 v[178:179], v204 offset:28672
	ds_read_b64_tr_b16 v[180:181], v205 offset:28672
	ds_read_b64_tr_b16 v[182:183], v206 offset:28672
	ds_read_b64_tr_b16 v[184:185], v207 offset:28672
	s_waitcnt lgkmcnt(14)
	v_mfma_f32_32x32x16_bf16 v[48:63], v[64:67], v[72:75], v[48:63]
	s_waitcnt lgkmcnt(12)
	v_mfma_f32_32x32x16_bf16 v[32:47], v[80:83], v[72:75], v[32:47]
	s_waitcnt lgkmcnt(10)
	v_mfma_f32_32x32x16_bf16 v[16:31], v[84:87], v[72:75], v[16:31]
	s_waitcnt lgkmcnt(8)
	v_mfma_f32_32x32x16_bf16 v[0:15], v[88:91], v[72:75], v[0:15]
	s_waitcnt lgkmcnt(6)
	v_mfma_f32_32x32x16_bf16 v[48:63], v[68:71], v[76:79], v[48:63]
	s_waitcnt lgkmcnt(4)
	v_mfma_f32_32x32x16_bf16 v[32:47], v[92:95], v[76:79], v[32:47]
	s_waitcnt lgkmcnt(2)
	v_mfma_f32_32x32x16_bf16 v[16:31], v[178:181], v[76:79], v[16:31]
	s_waitcnt lgkmcnt(0)
	v_mfma_f32_32x32x16_bf16 v[0:15], v[182:185], v[76:79], v[0:15]
	v_add_f32_e32 v173, v173, v187
